# attention tile loop: one merged rare-rescale test per sub-tile, rescale blocks out of line, common path falls through with a single back edge
# baseline (speedup 1.0000x reference)
.Lrare_s0:
	s_andn2_b64 vcc, exec, s[48:49]
	s_cbranch_vccnz .Lrare_s0b
	v_log_f32_e32 v129, v146
	s_nop 0
	v_max_f32_e32 v129, 0, v129
	v_exp_f32_e64 v130, -v129
	v_add_f32_e32 v190, v190, v129
	s_nop 1
	v_pk_mul_f32 v[126:127], v[130:131], v[126:127] op_sel_hi:[0,1]
	v_pk_mul_f32 v[124:125], v[130:131], v[124:125] op_sel_hi:[0,1]
	v_pk_mul_f32 v[122:123], v[130:131], v[122:123] op_sel_hi:[0,1]
	v_pk_mul_f32 v[120:121], v[130:131], v[120:121] op_sel_hi:[0,1]
	v_pk_mul_f32 v[118:119], v[130:131], v[118:119] op_sel_hi:[0,1]
	v_pk_mul_f32 v[116:117], v[130:131], v[116:117] op_sel_hi:[0,1]
	v_pk_mul_f32 v[114:115], v[130:131], v[114:115] op_sel_hi:[0,1]
	v_pk_mul_f32 v[112:113], v[130:131], v[112:113] op_sel_hi:[0,1]
	v_pk_mul_f32 v[94:95], v[130:131], v[94:95] op_sel_hi:[0,1]
	v_pk_mul_f32 v[92:93], v[130:131], v[92:93] op_sel_hi:[0,1]
	v_pk_mul_f32 v[90:91], v[130:131], v[90:91] op_sel_hi:[0,1]
	v_pk_mul_f32 v[88:89], v[130:131], v[88:89] op_sel_hi:[0,1]
	v_pk_mul_f32 v[86:87], v[130:131], v[86:87] op_sel_hi:[0,1]
	v_pk_mul_f32 v[84:85], v[130:131], v[84:85] op_sel_hi:[0,1]
	v_pk_mul_f32 v[82:83], v[130:131], v[82:83] op_sel_hi:[0,1]
	v_pk_mul_f32 v[80:81], v[130:131], v[80:81] op_sel_hi:[0,1]
	v_pk_mul_f32 v[62:63], v[130:131], v[62:63] op_sel_hi:[0,1]
	v_pk_mul_f32 v[60:61], v[130:131], v[60:61] op_sel_hi:[0,1]
	v_pk_mul_f32 v[58:59], v[130:131], v[58:59] op_sel_hi:[0,1]
	v_pk_mul_f32 v[56:57], v[130:131], v[56:57] op_sel_hi:[0,1]
	v_pk_mul_f32 v[54:55], v[130:131], v[54:55] op_sel_hi:[0,1]
	v_pk_mul_f32 v[52:53], v[130:131], v[52:53] op_sel_hi:[0,1]
	v_pk_mul_f32 v[50:51], v[130:131], v[50:51] op_sel_hi:[0,1]
	v_pk_mul_f32 v[48:49], v[130:131], v[48:49] op_sel_hi:[0,1]
	v_pk_mul_f32 v[30:31], v[130:131], v[30:31] op_sel_hi:[0,1]
	v_pk_mul_f32 v[28:29], v[130:131], v[28:29] op_sel_hi:[0,1]
	v_pk_mul_f32 v[26:27], v[130:131], v[26:27] op_sel_hi:[0,1]
	v_pk_mul_f32 v[24:25], v[130:131], v[24:25] op_sel_hi:[0,1]
	v_pk_mul_f32 v[22:23], v[130:131], v[22:23] op_sel_hi:[0,1]
	v_pk_mul_f32 v[20:21], v[130:131], v[20:21] op_sel_hi:[0,1]
	v_pk_mul_f32 v[18:19], v[130:131], v[18:19] op_sel_hi:[0,1]
	v_pk_mul_f32 v[16:17], v[130:131], v[16:17] op_sel_hi:[0,1]
	v_mul_f32_e32 v179, v179, v130

; #define LAS __attribute__((address_space(3)))
; __device__ __forceinline__ void dattn_unit(LAS unsigned char* lds, int b, int h, int qb, const bf16* Q, const bf16* K, const bf16* V, bf16* YB, float lam, const float* subg, float oml, int tid) {
;     ...
;     for (int t = 0; t < NT; ++t) {
;         if (t + 1 < NT) { const size_t adv = (size_t)(t + 1) * 64 * 1024; kr0 = *(const v4u*)(kg + adv); kr1 = *(const v4u*)(kg + adv + 64); vr0 = *(const v4u*)(vg + adv); vr1 = *(const v4u*)(vg + adv + 8); }
;         const LAS bf16* Ks = (const LAS bf16*)(lds + (t & 1) * AT_BUF + AT_KS); const LAS bf16* Vt = (const LAS bf16*)(lds + (t & 1) * AT_BUF + AT_VT);
;         const int kvbase = t * 64;
.Lrare_s1b:
	v_add_f32_e32 v181, v181, v128
	s_andn2_b64 vcc, exec, s[46:47]
	s_cbranch_vccnz .Lstage_nw
	v_log_f32_e32 v128, v144
	s_nop 0
	v_max_f32_e32 v129, 0, v128
	v_exp_f32_e64 v128, -v129
	v_add_f32_e32 v191, v191, v129
	v_pk_mul_f32 v[110:111], v[128:129], v[110:111] op_sel_hi:[0,1]
	v_pk_mul_f32 v[108:109], v[128:129], v[108:109] op_sel_hi:[0,1]
	v_pk_mul_f32 v[106:107], v[128:129], v[106:107] op_sel_hi:[0,1]
	v_pk_mul_f32 v[104:105], v[128:129], v[104:105] op_sel_hi:[0,1]
	v_pk_mul_f32 v[102:103], v[128:129], v[102:103] op_sel_hi:[0,1]
	v_pk_mul_f32 v[100:101], v[128:129], v[100:101] op_sel_hi:[0,1]
	v_pk_mul_f32 v[98:99], v[128:129], v[98:99] op_sel_hi:[0,1]
	v_pk_mul_f32 v[96:97], v[128:129], v[96:97] op_sel_hi:[0,1]
	v_pk_mul_f32 v[78:79], v[128:129], v[78:79] op_sel_hi:[0,1]
	v_pk_mul_f32 v[76:77], v[128:129], v[76:77] op_sel_hi:[0,1]
	v_pk_mul_f32 v[74:75], v[128:129], v[74:75] op_sel_hi:[0,1]
	v_pk_mul_f32 v[72:73], v[128:129], v[72:73] op_sel_hi:[0,1]
	v_pk_mul_f32 v[70:71], v[128:129], v[70:71] op_sel_hi:[0,1]
	v_pk_mul_f32 v[68:69], v[128:129], v[68:69] op_sel_hi:[0,1]
	v_pk_mul_f32 v[66:67], v[128:129], v[66:67] op_sel_hi:[0,1]
	v_pk_mul_f32 v[64:65], v[128:129], v[64:65] op_sel_hi:[0,1]
	v_pk_mul_f32 v[46:47], v[128:129], v[46:47] op_sel_hi:[0,1]
	v_pk_mul_f32 v[44:45], v[128:129], v[44:45] op_sel_hi:[0,1]
	v_pk_mul_f32 v[42:43], v[128:129], v[42:43] op_sel_hi:[0,1]
	v_pk_mul_f32 v[40:41], v[128:129], v[40:41] op_sel_hi:[0,1]
	v_pk_mul_f32 v[38:39], v[128:129], v[38:39] op_sel_hi:[0,1]
	v_pk_mul_f32 v[36:37], v[128:129], v[36:37] op_sel_hi:[0,1]
	v_pk_mul_f32 v[34:35], v[128:129], v[34:35] op_sel_hi:[0,1]
	v_pk_mul_f32 v[32:33], v[128:129], v[32:33] op_sel_hi:[0,1]
	v_pk_mul_f32 v[14:15], v[128:129], v[14:15] op_sel_hi:[0,1]
	v_pk_mul_f32 v[12:13], v[128:129], v[12:13] op_sel_hi:[0,1]
	v_pk_mul_f32 v[10:11], v[128:129], v[10:11] op_sel_hi:[0,1]
	v_pk_mul_f32 v[8:9], v[128:129], v[8:9] op_sel_hi:[0,1]
	v_pk_mul_f32 v[6:7], v[128:129], v[6:7] op_sel_hi:[0,1]
	v_pk_mul_f32 v[4:5], v[128:129], v[4:5] op_sel_hi:[0,1]
	v_pk_mul_f32 v[2:3], v[128:129], v[2:3] op_sel_hi:[0,1]
	v_pk_mul_f32 v[0:1], v[128:129], v[0:1] op_sel_hi:[0,1]
	v_mul_f32_e32 v181, v181, v128
	s_branch .Lstage_nw
.Lstage_nw:
	s_add_i32 s59, s59, 1
	s_bitcmp1_b32 s59, 0
	s_cselect_b32 s18, 0x9000, 0
	s_add_i32 s60, s18, 0
	s_addk_i32 s57, 0x100
	s_add_i32 s58, s58, 64
	s_add_u32 s98, s98, s14
	s_addc_u32 s99, s99, s15
	s_add_u32 s100, s100, s14
	s_addc_u32 s101, s101, s15
	s_cmp_lg_u32 s56, s57
	s_branch .Lstage_join

; #define LAS __attribute__((address_space(3)))
; #define AT_RAISE(MP) do { if (trig[MP]) { const float dl = fmaxf(__builtin_amdgcn_logf(pmx[MP]), 0.f), al = __builtin_amdgcn_exp2f(-dl); mref[MP] += dl; lsum[MP] *= al; \
;                 _Pragma("unroll") for (int cb = 0; cb < 4; ++cb) o[MP][cb] = o[MP][cb] * al; } } while (0)
; __device__ __forceinline__ void dattn_unit(LAS unsigned char* lds, int b, int h, int qb, const bf16* Q, const bf16* K, const bf16* V, bf16* YB, float lam, const float* subg, float oml, int tid) {
;     ...
;             bf16x8 pA0, pB0, pA1, pB1; bool trig[2]; float pmx[2] = {1.f, 1.f};
;             AT_SOFTMAX(s0, 0, pA0, pB0);
;             AT_SOFTMAX(s1, 1, pA1, pB1);
; #pragma unroll
;             for (int cb = 0; cb < 4; ++cb) { const LAS bf16* vp = Vt + (32 * cb + ql) * 72 + 32 * sub + 4 * hi;
;                 const v2u a0 = *(const LAS v2u*)(vp), a1 = *(const LAS v2u*)(vp + 8), a2 = *(const LAS v2u*)(vp + 16), a3 = *(const LAS v2u*)(vp + 24);
;                 const v4u f0 = {a0.x, a0.y, a1.x, a1.y}, f1 = {a2.x, a2.y, a3.x, a3.y};
;                 o[0][cb] = __builtin_amdgcn_mfma_f32_32x32x16_bf16(__builtin_bit_cast(bf16x8, f0), pA0, o[0][cb], 0, 0, 0);
;                 o[1][cb] = __builtin_amdgcn_mfma_f32_32x32x16_bf16(__builtin_bit_cast(bf16x8, f0), pA1, o[1][cb], 0, 0, 0);
;                 o[0][cb] = __builtin_amdgcn_mfma_f32_32x32x16_bf16(__builtin_bit_cast(bf16x8, f1), pB0, o[0][cb], 0, 0, 0);
;                 o[1][cb] = __builtin_amdgcn_mfma_f32_32x32x16_bf16(__builtin_bit_cast(bf16x8, f1), pB1, o[1][cb], 0, 0, 0); }
;             AT_RAISE(0); AT_RAISE(1);
.LBB0_234:
	v_cvt_pk_bf16_f32 v152, v155, v129
	v_cvt_pk_bf16_f32 v153, v130, v131
	v_cvt_pk_bf16_f32 v154, v132, v156
	v_cvt_pk_bf16_f32 v155, v157, v158
	v_cvt_pk_bf16_f32 v130, v133, v134
	v_cvt_pk_bf16_f32 v131, v135, v136
	v_cvt_pk_bf16_f32 v132, v137, v138
	v_cvt_pk_bf16_f32 v133, v139, v140
	s_andn2_b64 vcc, exec, s[48:49]
	s_nop 0
	v_mfma_f32_32x32x16_bf16 v[64:79], v[228:231], v[152:155], v[64:79]
	ds_read_b128 v[138:141], v199 offset:4608
	v_mfma_f32_32x32x16_bf16 v[64:79], v[232:235], v[130:133], v[64:79]
	v_mfma_f32_32x32x16_bf16 v[32:47], v[236:239], v[152:155], v[32:47]
	v_mfma_f32_32x32x16_bf16 v[32:47], v[240:243], v[130:133], v[32:47]
	v_mfma_f32_32x32x16_bf16 v[96:111], v[220:223], v[152:155], v[96:111]
	ds_read_b128 v[218:221], v189
	ds_read_b128 v[222:225], v189 offset:4096
	v_mfma_f32_32x32x16_bf16 v[96:111], v[204:207], v[130:133], v[96:111]
	ds_read_b128 v[204:207], v199 offset:13824
	ds_read_b128 v[226:229], v199 offset:4640
	ds_read_b128 v[230:233], v199 offset:13856
	v_mfma_f32_32x32x16_bf16 v[0:15], v[212:215], v[152:155], v[0:15]
	ds_read_b128 v[234:237], v189 offset:1024
	ds_read_b128 v[238:241], v189 offset:5120
	v_mfma_f32_32x32x16_bf16 v[0:15], v[200:203], v[130:133], v[0:15]
	s_or_b64 vcc, s[48:49], s[46:47]
	s_cbranch_vccnz .Lrare_s0
	v_add_f32_e32 v181, v181, v128

; #define LAS __attribute__((address_space(3)))
; #define AT_RAISE(MP) do { if (trig[MP]) { const float dl = fmaxf(__builtin_amdgcn_logf(pmx[MP]), 0.f), al = __builtin_amdgcn_exp2f(-dl); mref[MP] += dl; lsum[MP] *= al; \
;                 _Pragma("unroll") for (int cb = 0; cb < 4; ++cb) o[MP][cb] = o[MP][cb] * al; } } while (0)
; __device__ __forceinline__ void dattn_unit(LAS unsigned char* lds, int b, int h, int qb, const bf16* Q, const bf16* K, const bf16* V, bf16* YB, float lam, const float* subg, float oml, int tid) {
;     ...
;             bf16x8 pA0, pB0, pA1, pB1; bool trig[2]; float pmx[2] = {1.f, 1.f};
;             AT_SOFTMAX(s0, 0, pA0, pB0);
;             AT_SOFTMAX(s1, 1, pA1, pB1);
; #pragma unroll
;             for (int cb = 0; cb < 4; ++cb) { const LAS bf16* vp = Vt + (32 * cb + ql) * 72 + 32 * sub + 4 * hi;
;                 const v2u a0 = *(const LAS v2u*)(vp), a1 = *(const LAS v2u*)(vp + 8), a2 = *(const LAS v2u*)(vp + 16), a3 = *(const LAS v2u*)(vp + 24);
;                 const v4u f0 = {a0.x, a0.y, a1.x, a1.y}, f1 = {a2.x, a2.y, a3.x, a3.y};
;                 o[0][cb] = __builtin_amdgcn_mfma_f32_32x32x16_bf16(__builtin_bit_cast(bf16x8, f0), pA0, o[0][cb], 0, 0, 0);
;                 o[1][cb] = __builtin_amdgcn_mfma_f32_32x32x16_bf16(__builtin_bit_cast(bf16x8, f0), pA1, o[1][cb], 0, 0, 0);
;                 o[0][cb] = __builtin_amdgcn_mfma_f32_32x32x16_bf16(__builtin_bit_cast(bf16x8, f1), pB0, o[0][cb], 0, 0, 0);
;                 o[1][cb] = __builtin_amdgcn_mfma_f32_32x32x16_bf16(__builtin_bit_cast(bf16x8, f1), pB1, o[1][cb], 0, 0, 0); }
;             AT_RAISE(0); AT_RAISE(1);
;         }
;     ...
;         }
;         if (t + 1 < NT) AT_STAGE((t + 1) & 1);
;         __syncthreads();
.LBB0_245:
	v_cvt_pk_bf16_f32 v152, v155, v129
	v_cvt_pk_bf16_f32 v153, v130, v131
	v_cvt_pk_bf16_f32 v154, v132, v156
	v_cvt_pk_bf16_f32 v155, v157, v158
	v_cvt_pk_bf16_f32 v130, v133, v134
	v_cvt_pk_bf16_f32 v131, v135, v136
	v_cvt_pk_bf16_f32 v132, v137, v138
	v_cvt_pk_bf16_f32 v133, v139, v140
	s_xor_b32 s18, s38, 0x9000
	v_add3_u32 v148, s18, v196, v180
	v_add3_u32 v149, s18, v197, v195
	s_andn2_b64 vcc, exec, s[48:49]
	s_nop 0
	v_mfma_f32_32x32x16_bf16 v[64:79], v[222:225], v[152:155], v[64:79]
	s_waitcnt vmcnt(3)
	ds_write_b128 v148, v[168:171]
	v_mfma_f32_32x32x16_bf16 v[64:79], v[226:229], v[130:133], v[64:79]
	s_waitcnt vmcnt(2)
	ds_write_b128 v148, v[172:175] offset:9216
	v_mfma_f32_32x32x16_bf16 v[32:47], v[230:233], v[152:155], v[32:47]
	s_waitcnt vmcnt(1)
	ds_write_b16 v149, v164 offset:18432
	ds_write_b16_d16_hi v149, v164 offset:18576
	ds_write_b16 v149, v165 offset:18720
	v_mfma_f32_32x32x16_bf16 v[32:47], v[234:237], v[130:133], v[32:47]
	ds_write_b16_d16_hi v149, v165 offset:18864
	ds_write_b16 v149, v166 offset:19008
	ds_write_b16_d16_hi v149, v166 offset:19152
	v_mfma_f32_32x32x16_bf16 v[96:111], v[212:215], v[152:155], v[96:111]
	ds_write_b16 v149, v167 offset:19296
	ds_write_b16_d16_hi v149, v167 offset:19440
	s_waitcnt vmcnt(0)
	ds_write_b16 v149, v160 offset:19584
	v_mfma_f32_32x32x16_bf16 v[96:111], v[200:203], v[130:133], v[96:111]
	ds_write_b16_d16_hi v149, v160 offset:19728
	ds_write_b16 v149, v161 offset:19872
	ds_write_b16_d16_hi v149, v161 offset:20016
	v_mfma_f32_32x32x16_bf16 v[0:15], v[238:241], v[152:155], v[0:15]
	ds_write_b16 v149, v162 offset:20160
	ds_write_b16_d16_hi v149, v162 offset:20304
	v_mfma_f32_32x32x16_bf16 v[0:15], v[218:221], v[130:133], v[0:15]
	ds_write_b16 v149, v163 offset:20448
	ds_write_b16_d16_hi v149, v163 offset:20592
	s_or_b64 vcc, s[48:49], s[46:47]
	s_cbranch_vccnz .Lrare_s1
	v_add_f32_e32 v181, v181, v128
	s_add_i32 s59, s59, 1
	s_bitcmp1_b32 s59, 0
	s_cselect_b32 s18, 0x9000, 0
	s_add_i32 s60, s18, 0
	s_addk_i32 s57, 0x100
	s_add_i32 s58, s58, 64
	s_add_u32 s98, s98, s14
	s_addc_u32 s99, s99, s15
	s_add_u32 s100, s100, s14
	s_addc_u32 s101, s101, s15
	s_cmp_lg_u32 s56, s57
	s_waitcnt lgkmcnt(0)
	s_barrier
	s_cbranch_scc1 .LBB0_227
